# speedup vs baseline: 1.0222x; 1.0053x over previous
;   __device__ __forceinline__ u16* wt() const { return (u16*)(ws); }
;   if (ldb == 0) ldb = K;
;   float* lds = (float*)shm;
;   const int nTn = N >> 6;
;   const int tk = tile / nTn, tn = tile - tk * nTn;
;   const int k0 = tk * 64, n0 = tn * 64;
;   const int tid = opaque_tid(wv);
;   {
;     const int r = tid >> 4, c4 = (tid & 15) * 4;
; #pragma unroll
;     for (int i = 0; i < 2; ++i) {
;       float4 v = *(const float4*)(W + (long)(k0 + r + 32 * i) * N + n0 + c4);
;       float* d = lds + (r + 32 * i) * 65 + c4;
;       d[0] = v.x; d[1] = v.y; d[2] = v.z; d[3] = v.w;
;     }
;   }
;   __syncthreads();
;   {
;     const int n = tid >> 3, kq = (tid & 7) * 8;
;     float f[8];
; #pragma unroll
;     for (int j = 0; j < 8; ++j) f[j] = lds[(kq + j) * 65 + n];
;     if (gain) {
; #pragma unroll
;       for (int j = 0; j < 8; ++j) f[j] *= gain[k0 + kq + j];
;     }
;     u32x4 o = {pack2(f[0], f[1]), pack2(f[2], f[3]), pack2(f[4], f[5]), pack2(f[6], f[7])};
;     *(u32x4*)(Bt + (long)(n0 + n) * ldb + k0 + kq) = o;
;   }
;   __syncthreads();
; }
; __device__ __forceinline__ void convert_weights(const Params& p, int l, char* shm, int wv) {
;   u16* wb = p.wt() + (long)(l & 1) * WT_SET;
;   for (int g = opaque_bid(); g < 3648; g += gridDim.x) {
;     if (g < 1088) convert_tile(p.w_in + (long)l * 1024 * 4352, wb + O_IN, 1024, 4352, g, shm, p.mix_g + l * DM, wv);
;     else if (g < 1216) convert_tile(p.w_bsb + (long)l * 512 * 1024, wb + O_BSB, 512, 1024, g - 1088, shm, nullptr, wv, 1024);
;     else if (g < 1344) convert_tile(p.w_bswa + (long)l * 512 * 1024, wb + O_BSB + 512, 512, 1024, g - 1216, shm, nullptr, wv, 1024);
;     else if (g < 1600) convert_tile(p.w_out + (long)l * 1024 * 1024, wb + O_OUT, 1024, 1024, g - 1344, shm, nullptr, wv);
;     else if (g < 2624) convert_tile(p.w_up + (long)l * 1024 * 4096, wb + O_UP, 1024, 4096, g - 1600, shm, p.mlp_g + l * DM, wv);
;     else convert_tile(p.w_down + (long)l * 4096 * 1024, wb + O_DOWN, 4096, 1024, g - 2624, shm, nullptr, wv);
.LBB0_4:
	s_add_i32 s36, s20, 0xa40
	s_cmpk_gt_i32 s36, 0x43f
	s_mov_b64 s[16:17], -1
	s_cbranch_scc0 .LBB0_24
	s_cmpk_gt_u32 s36, 0x4bf
	s_cbranch_scc0 .LBB0_21
	s_cmpk_gt_u32 s36, 0x53f
	s_cbranch_scc0 .LBB0_18
	s_cmpk_gt_u32 s36, 0x63f
	s_cbranch_scc0 .LBB0_15
	s_cmpk_gt_u32 s36, 0xa3f
	s_cbranch_scc0 .LBB0_10
	s_lshr_b32 s14, s20, 4
	s_lshl_b32 s16, s14, 10
	s_sub_i32 s16, s21, s16
	v_mbcnt_lo_u32_b32 v2, -1, 0
	v_mbcnt_hi_u32_b32 v2, -1, v2
	s_ashr_i32 s17, s16, 31
	v_add_u32_e32 v12, s84, v2
	s_lshl_b64 s[38:39], s[16:17], 2
	v_ashrrev_i32_e32 v13, 4, v12
	v_lshl_add_u32 v4, s14, 6, v13
	s_add_u32 s38, s62, s38
	v_lshlrev_b32_e32 v2, 4, v12
	s_addc_u32 s39, s63, s39
	v_and_b32_e32 v2, 0xf0, v2
	v_ashrrev_i32_e32 v5, 31, v4
	v_lshl_add_u64 v[6:7], s[38:39], 0, v[2:3]
	v_lshlrev_b64 v[4:5], 12, v[4:5]
	v_lshl_add_u64 v[8:9], v[6:7], 0, v[4:5]
	global_load_dwordx4 v[4:7], v[8:9], off nt
	v_add_co_u32_e32 v8, vcc, s27, v8
	v_ashrrev_i32_e32 v16, 3, v12
	s_nop 0
	v_addc_co_u32_e32 v9, vcc, 0, v9, vcc
	global_load_dwordx4 v[8:11], v[8:9], off nt
	v_lshlrev_b32_e32 v12, 3, v12
	v_and_b32_e32 v17, 56, v12
	v_add_u32_e32 v12, s16, v16
	v_mad_u64_u32 v[14:15], s[16:17], v13, s26, v[2:3]
	v_mul_u32_u24_e32 v2, 0x104, v17
	v_lshl_add_u32 v16, v16, 2, v2
	v_add_u32_e32 v15, 0x2080, v14
	v_add_u32_e32 v18, 0x2088, v14
	v_add_u32_e32 v19, 0x400, v16
	v_ashrrev_i32_e32 v13, 31, v12
	v_lshlrev_b64 v[12:13], 13, v[12:13]
	s_lshl_b32 s14, s14, 7
	v_lshl_add_u64 v[12:13], s[0:1], 0, v[12:13]
	v_lshlrev_b32_e32 v2, 1, v17
	v_lshl_add_u64 v[12:13], v[12:13], 0, s[14:15]
	v_lshl_add_u64 v[12:13], v[12:13], 0, v[2:3]
	s_mov_b64 s[16:17], 0
	s_waitcnt vmcnt(1)
	ds_write2_b32 v14, v4, v5 offset1:1
	ds_write2_b32 v14, v6, v7 offset0:2 offset1:3
	s_waitcnt vmcnt(0)
	ds_write2_b32 v15, v8, v9 offset1:1
	ds_write2_b32 v18, v10, v11 offset1:1
	s_waitcnt lgkmcnt(0)
	s_barrier
	ds_read2_b32 v[4:5], v16 offset1:65
	ds_read2_b32 v[6:7], v16 offset0:130 offset1:195
	ds_read2_b32 v[8:9], v19 offset0:4 offset1:69
	ds_read2_b32 v[10:11], v19 offset0:134 offset1:199
	s_waitcnt lgkmcnt(3)
	v_cvt_pk_bf16_f32 v4, v4, v5
	s_waitcnt lgkmcnt(2)
	v_cvt_pk_bf16_f32 v5, v6, v7
	s_waitcnt lgkmcnt(1)
	v_cvt_pk_bf16_f32 v6, v8, v9
	s_waitcnt lgkmcnt(0)
	v_cvt_pk_bf16_f32 v7, v10, v11
	global_store_dwordx4 v[12:13], v[4:7], off
	s_barrier
.LBB0_10:
	s_andn2_b64 vcc, exec, s[16:17]
	s_cbranch_vccnz .LBB0_14
	s_add_i32 s16, s21, 0x10000
	s_add_i32 s14, s20, 0x400
	s_and_b32 s16, s16, 0xfc0
	v_mbcnt_lo_u32_b32 v2, -1, 0
	v_mbcnt_hi_u32_b32 v2, -1, v2
	s_andn2_b32 s14, s14, 63
	v_add_u32_e32 v12, s84, v2
	s_lshl_b32 s17, s16, 2
	v_ashrrev_i32_e32 v14, 4, v12
	v_add_u32_e32 v4, s14, v14
	s_add_u32 s38, s60, s17
	v_lshlrev_b32_e32 v2, 4, v12
	s_addc_u32 s39, s61, 0
	v_and_b32_e32 v2, 0xf0, v2
	v_ashrrev_i32_e32 v5, 31, v4
	v_lshl_add_u64 v[6:7], s[38:39], 0, v[2:3]
	v_lshlrev_b64 v[4:5], 14, v[4:5]
	v_lshl_add_u64 v[8:9], v[6:7], 0, v[4:5]
	global_load_dwordx4 v[4:7], v[8:9], off nt
	v_add_co_u32_e32 v8, vcc, s34, v8
	v_ashrrev_i32_e32 v13, 3, v12
	s_nop 0
	v_addc_co_u32_e32 v9, vcc, 0, v9, vcc
	global_load_dwordx4 v[8:11], v[8:9], off nt
	v_lshlrev_b32_e32 v12, 3, v12
	v_and_b32_e32 v12, 56, v12
	v_mad_u64_u32 v[14:15], s[38:39], v14, s26, v[2:3]
	v_mul_u32_u24_e32 v2, 0x104, v12
	v_lshl_add_u32 v2, v13, 2, v2
	v_add_u32_e32 v15, 0x2080, v14
	v_add_u32_e32 v16, 0x2088, v14
	v_add_u32_e32 v17, 0x400, v2
	s_andn2_b64 vcc, exec, s[10:11]
	s_waitcnt vmcnt(1)
	ds_write2_b32 v14, v4, v5 offset1:1
	ds_write2_b32 v14, v6, v7 offset0:2 offset1:3
	s_waitcnt vmcnt(0)
	ds_write2_b32 v15, v8, v9 offset1:1
	ds_write2_b32 v16, v10, v11 offset1:1
	s_waitcnt lgkmcnt(0)
	s_barrier
	ds_read2_b32 v[4:5], v2 offset1:65
	ds_read2_b32 v[6:7], v2 offset0:130 offset1:195
	ds_read2_b32 v[8:9], v17 offset0:4 offset1:69
	ds_read2_b32 v[10:11], v17 offset0:134 offset1:199
	s_cbranch_vccnz .LBB0_13
	v_or_b32_e32 v2, s14, v12
	v_lshl_add_u64 v[18:19], v[2:3], 2, s[58:59]
	global_load_dwordx4 v[14:17], v[18:19], off nt
	s_nop 0
	global_load_dwordx4 v[18:21], v[18:19], off offset:16
	s_waitcnt vmcnt(1) lgkmcnt(3)
	v_pk_mul_f32 v[4:5], v[4:5], v[14:15]
	s_waitcnt lgkmcnt(2)
	v_pk_mul_f32 v[6:7], v[6:7], v[16:17]
	s_waitcnt vmcnt(0) lgkmcnt(1)
	v_pk_mul_f32 v[8:9], v[8:9], v[18:19]
	s_waitcnt lgkmcnt(0)
	v_pk_mul_f32 v[10:11], v[10:11], v[20:21]

;   if (ldb == 0) ldb = K;
;   float* lds = (float*)shm;
;   const int nTn = N >> 6;
;   const int tk = tile / nTn, tn = tile - tk * nTn;
;   const int k0 = tk * 64, n0 = tn * 64;
;   const int tid = opaque_tid(wv);
;   {
;     const int r = tid >> 4, c4 = (tid & 15) * 4;
; #pragma unroll
;     for (int i = 0; i < 2; ++i) {
;       float4 v = *(const float4*)(W + (long)(k0 + r + 32 * i) * N + n0 + c4);
;       float* d = lds + (r + 32 * i) * 65 + c4;
;       d[0] = v.x; d[1] = v.y; d[2] = v.z; d[3] = v.w;
;     }
;   }
;   __syncthreads();
;   {
;     const int n = tid >> 3, kq = (tid & 7) * 8;
;     float f[8];
; #pragma unroll
;     for (int j = 0; j < 8; ++j) f[j] = lds[(kq + j) * 65 + n];
;     if (gain) {
; #pragma unroll
;       for (int j = 0; j < 8; ++j) f[j] *= gain[k0 + kq + j];
;     }
;     u32x4 o = {pack2(f[0], f[1]), pack2(f[2], f[3]), pack2(f[4], f[5]), pack2(f[6], f[7])};
;     *(u32x4*)(Bt + (long)(n0 + n) * ldb + k0 + kq) = o;
;   }
;   __syncthreads();
; }
.LBB0_15:
	s_andn2_b64 vcc, exec, s[16:17]
	s_cbranch_vccnz .LBB0_17
	s_lshl_b32 s14, s23, 6
	s_and_b32 s16, s14, 0xfffffc00
	s_sub_i32 s16, s21, s16
	s_lshl_b32 s14, s20, 2
	s_add_i32 s16, s16, 0x14000
	s_addk_i32 s14, 0x1400
	v_mbcnt_lo_u32_b32 v2, -1, 0
	v_mbcnt_hi_u32_b32 v2, -1, v2
	s_ashr_i32 s17, s16, 31
	v_add_u32_e32 v12, s84, v2
	s_andn2_b32 s14, s14, 63
	s_lshl_b64 s[38:39], s[16:17], 2
	v_ashrrev_i32_e32 v13, 4, v12
	v_add_u32_e32 v4, s14, v13
	s_add_u32 s38, s56, s38
	v_lshlrev_b32_e32 v2, 4, v12
	s_addc_u32 s39, s57, s39
	v_and_b32_e32 v2, 0xf0, v2
	v_ashrrev_i32_e32 v5, 31, v4
	v_lshl_add_u64 v[6:7], s[38:39], 0, v[2:3]
	v_lshlrev_b64 v[4:5], 12, v[4:5]
	v_lshl_add_u64 v[8:9], v[6:7], 0, v[4:5]
	global_load_dwordx4 v[4:7], v[8:9], off nt
	v_add_co_u32_e32 v8, vcc, s27, v8
	v_ashrrev_i32_e32 v16, 3, v12
	s_nop 0
	v_addc_co_u32_e32 v9, vcc, 0, v9, vcc
	global_load_dwordx4 v[8:11], v[8:9], off nt
	v_lshlrev_b32_e32 v12, 3, v12
	v_and_b32_e32 v17, 56, v12
	v_add_u32_e32 v12, s16, v16
	v_mad_u64_u32 v[14:15], s[16:17], v13, s26, v[2:3]
	v_mul_u32_u24_e32 v2, 0x104, v17
	v_lshl_add_u32 v16, v16, 2, v2
	v_add_u32_e32 v15, 0x2080, v14
	v_add_u32_e32 v18, 0x2088, v14
	v_add_u32_e32 v19, 0x400, v16
	v_ashrrev_i32_e32 v13, 31, v12
	v_lshlrev_b64 v[12:13], 11, v[12:13]
	v_lshl_add_u64 v[12:13], s[4:5], 0, v[12:13]
	v_lshl_add_u64 v[12:13], s[14:15], 1, v[12:13]
	v_lshlrev_b32_e32 v2, 1, v17
	v_lshl_add_u64 v[12:13], v[12:13], 0, v[2:3]
	s_waitcnt vmcnt(1)
	ds_write2_b32 v14, v4, v5 offset1:1
	ds_write2_b32 v14, v6, v7 offset0:2 offset1:3
	s_waitcnt vmcnt(0)
	ds_write2_b32 v15, v8, v9 offset1:1
	ds_write2_b32 v18, v10, v11 offset1:1
	s_waitcnt lgkmcnt(0)
	s_barrier
	ds_read2_b32 v[4:5], v16 offset1:65
	ds_read2_b32 v[6:7], v16 offset0:130 offset1:195
	ds_read2_b32 v[8:9], v19 offset0:4 offset1:69
	ds_read2_b32 v[10:11], v19 offset0:134 offset1:199
	s_waitcnt lgkmcnt(3)
	v_cvt_pk_bf16_f32 v4, v4, v5
	s_waitcnt lgkmcnt(2)
	v_cvt_pk_bf16_f32 v5, v6, v7
	s_waitcnt lgkmcnt(1)
	v_cvt_pk_bf16_f32 v6, v8, v9
	s_waitcnt lgkmcnt(0)
	v_cvt_pk_bf16_f32 v7, v10, v11
	global_store_dwordx4 v[12:13], v[4:7], off
	s_barrier

;   if (ldb == 0) ldb = K;
;   float* lds = (float*)shm;
;   const int nTn = N >> 6;
;   const int tk = tile / nTn, tn = tile - tk * nTn;
;   const int k0 = tk * 64, n0 = tn * 64;
;   const int tid = opaque_tid(wv);
;   {
;     const int r = tid >> 4, c4 = (tid & 15) * 4;
; #pragma unroll
;     for (int i = 0; i < 2; ++i) {
;       float4 v = *(const float4*)(W + (long)(k0 + r + 32 * i) * N + n0 + c4);
;       float* d = lds + (r + 32 * i) * 65 + c4;
;       d[0] = v.x; d[1] = v.y; d[2] = v.z; d[3] = v.w;
;     }
;   }
;   __syncthreads();
;   {
;     const int n = tid >> 3, kq = (tid & 7) * 8;
;     float f[8];
; #pragma unroll
;     for (int j = 0; j < 8; ++j) f[j] = lds[(kq + j) * 65 + n];
;     if (gain) {
; #pragma unroll
;       for (int j = 0; j < 8; ++j) f[j] *= gain[k0 + kq + j];
;     }
;     u32x4 o = {pack2(f[0], f[1]), pack2(f[2], f[3]), pack2(f[4], f[5]), pack2(f[6], f[7])};
;     *(u32x4*)(Bt + (long)(n0 + n) * ldb + k0 + kq) = o;
;   }
;   __syncthreads();
; }
.LBB0_18:
	s_andn2_b64 vcc, exec, s[16:17]
	s_cbranch_vccnz .LBB0_20
	s_lshl_b32 s16, s24, 6
	s_and_b32 s16, s16, 0xfffffc00
	s_sub_i32 s16, s21, s16
	s_lshl_b32 s14, s20, 2
	s_add_i32 s16, s16, 0x16000
	s_addk_i32 s14, 0x1600
	v_mbcnt_lo_u32_b32 v2, -1, 0
	v_mbcnt_hi_u32_b32 v2, -1, v2
	s_ashr_i32 s17, s16, 31
	v_add_u32_e32 v12, s84, v2
	s_andn2_b32 s14, s14, 63
	s_lshl_b64 s[38:39], s[16:17], 2
	v_ashrrev_i32_e32 v13, 4, v12
	v_add_u32_e32 v4, s14, v13
	s_add_u32 s38, s54, s38
	v_lshlrev_b32_e32 v2, 4, v12
	s_addc_u32 s39, s55, s39
	v_and_b32_e32 v2, 0xf0, v2
	v_ashrrev_i32_e32 v5, 31, v4
	v_lshl_add_u64 v[6:7], s[38:39], 0, v[2:3]
	v_lshlrev_b64 v[4:5], 12, v[4:5]
	v_lshl_add_u64 v[8:9], v[6:7], 0, v[4:5]
	global_load_dwordx4 v[4:7], v[8:9], off nt
	v_add_co_u32_e32 v8, vcc, s27, v8
	v_ashrrev_i32_e32 v16, 3, v12
	s_nop 0
	v_addc_co_u32_e32 v9, vcc, 0, v9, vcc
	global_load_dwordx4 v[8:11], v[8:9], off nt
	v_lshlrev_b32_e32 v12, 3, v12
	v_and_b32_e32 v17, 56, v12
	v_add_u32_e32 v12, s16, v16
	v_mad_u64_u32 v[14:15], s[16:17], v13, s26, v[2:3]
	v_mul_u32_u24_e32 v2, 0x104, v17
	v_lshl_add_u32 v16, v16, 2, v2
	v_add_u32_e32 v15, 0x2080, v14
	v_add_u32_e32 v18, 0x2088, v14
	v_add_u32_e32 v19, 0x400, v16
	v_ashrrev_i32_e32 v13, 31, v12
	v_lshlrev_b64 v[12:13], 11, v[12:13]
	v_lshl_add_u64 v[12:13], s[6:7], 0, v[12:13]
	v_lshl_add_u64 v[12:13], s[14:15], 1, v[12:13]
	v_lshlrev_b32_e32 v2, 1, v17
	v_lshl_add_u64 v[12:13], v[12:13], 0, v[2:3]
	s_waitcnt vmcnt(1)
	ds_write2_b32 v14, v4, v5 offset1:1
	ds_write2_b32 v14, v6, v7 offset0:2 offset1:3
	s_waitcnt vmcnt(0)
	ds_write2_b32 v15, v8, v9 offset1:1
	ds_write2_b32 v18, v10, v11 offset1:1
	s_waitcnt lgkmcnt(0)
	s_barrier
	ds_read2_b32 v[4:5], v16 offset1:65
	ds_read2_b32 v[6:7], v16 offset0:130 offset1:195
	ds_read2_b32 v[8:9], v19 offset0:4 offset1:69
	ds_read2_b32 v[10:11], v19 offset0:134 offset1:199
	s_waitcnt lgkmcnt(3)
	v_cvt_pk_bf16_f32 v4, v4, v5
	s_waitcnt lgkmcnt(2)
	v_cvt_pk_bf16_f32 v5, v6, v7
	s_waitcnt lgkmcnt(1)
	v_cvt_pk_bf16_f32 v6, v8, v9
	s_waitcnt lgkmcnt(0)
	v_cvt_pk_bf16_f32 v7, v10, v11
	global_store_dwordx4 v[12:13], v[4:7], off
	s_barrier

;   if (ldb == 0) ldb = K;
;   float* lds = (float*)shm;
;   const int nTn = N >> 6;
;   const int tk = tile / nTn, tn = tile - tk * nTn;
;   const int k0 = tk * 64, n0 = tn * 64;
;   const int tid = opaque_tid(wv);
;   {
;     const int r = tid >> 4, c4 = (tid & 15) * 4;
; #pragma unroll
;     for (int i = 0; i < 2; ++i) {
;       float4 v = *(const float4*)(W + (long)(k0 + r + 32 * i) * N + n0 + c4);
;       float* d = lds + (r + 32 * i) * 65 + c4;
;       d[0] = v.x; d[1] = v.y; d[2] = v.z; d[3] = v.w;
;     }
;   }
;   __syncthreads();
;   {
;     const int n = tid >> 3, kq = (tid & 7) * 8;
;     float f[8];
; #pragma unroll
;     for (int j = 0; j < 8; ++j) f[j] = lds[(kq + j) * 65 + n];
;     if (gain) {
; #pragma unroll
;       for (int j = 0; j < 8; ++j) f[j] *= gain[k0 + kq + j];
;     }
;     u32x4 o = {pack2(f[0], f[1]), pack2(f[2], f[3]), pack2(f[4], f[5]), pack2(f[6], f[7])};
;     *(u32x4*)(Bt + (long)(n0 + n) * ldb + k0 + kq) = o;
;   }
;   __syncthreads();
; }
.LBB0_21:
	s_andn2_b64 vcc, exec, s[16:17]
	s_cbranch_vccnz .LBB0_23
	s_lshl_b32 s14, s25, 6
	s_and_b32 s16, s14, 0xfffffc00
	s_sub_i32 s16, s21, s16
	s_lshl_b32 s14, s20, 2
	s_add_i32 s16, s16, 0x18000
	s_addk_i32 s14, 0x1800
	v_mbcnt_lo_u32_b32 v2, -1, 0
	v_mbcnt_hi_u32_b32 v2, -1, v2
	s_ashr_i32 s17, s16, 31
	v_add_u32_e32 v12, s84, v2
	s_andn2_b32 s14, s14, 63
	s_lshl_b64 s[38:39], s[16:17], 2
	v_ashrrev_i32_e32 v13, 4, v12
	v_add_u32_e32 v4, s14, v13
	s_add_u32 s38, s52, s38
	v_lshlrev_b32_e32 v2, 4, v12
	s_addc_u32 s39, s53, s39
	v_and_b32_e32 v2, 0xf0, v2
	v_ashrrev_i32_e32 v5, 31, v4
	v_lshl_add_u64 v[6:7], s[38:39], 0, v[2:3]
	v_lshlrev_b64 v[4:5], 12, v[4:5]
	v_lshl_add_u64 v[8:9], v[6:7], 0, v[4:5]
	global_load_dwordx4 v[4:7], v[8:9], off nt
	v_add_co_u32_e32 v8, vcc, s27, v8
	v_ashrrev_i32_e32 v16, 3, v12
	s_nop 0
	v_addc_co_u32_e32 v9, vcc, 0, v9, vcc
	global_load_dwordx4 v[8:11], v[8:9], off nt
	v_lshlrev_b32_e32 v12, 3, v12
	v_and_b32_e32 v17, 56, v12
	v_add_u32_e32 v12, s16, v16
	v_mad_u64_u32 v[14:15], s[16:17], v13, s26, v[2:3]
	v_mul_u32_u24_e32 v2, 0x104, v17
	v_lshl_add_u32 v16, v16, 2, v2
	v_add_u32_e32 v15, 0x2080, v14
	v_add_u32_e32 v18, 0x2088, v14
	v_add_u32_e32 v19, 0x400, v16
	v_ashrrev_i32_e32 v13, 31, v12
	v_lshlrev_b64 v[12:13], 11, v[12:13]
	v_lshl_add_u64 v[12:13], s[8:9], 0, v[12:13]
	v_lshl_add_u64 v[12:13], s[14:15], 1, v[12:13]
	v_lshlrev_b32_e32 v2, 1, v17
	v_lshl_add_u64 v[12:13], v[12:13], 0, v[2:3]
	s_waitcnt vmcnt(1)
	ds_write2_b32 v14, v4, v5 offset1:1
	ds_write2_b32 v14, v6, v7 offset0:2 offset1:3
	s_waitcnt vmcnt(0)
	ds_write2_b32 v15, v8, v9 offset1:1
	ds_write2_b32 v18, v10, v11 offset1:1
	s_waitcnt lgkmcnt(0)
	s_barrier
	ds_read2_b32 v[4:5], v16 offset1:65
	ds_read2_b32 v[6:7], v16 offset0:130 offset1:195
	ds_read2_b32 v[8:9], v19 offset0:4 offset1:69
	ds_read2_b32 v[10:11], v19 offset0:134 offset1:199
	s_waitcnt lgkmcnt(3)
	v_cvt_pk_bf16_f32 v4, v4, v5
	s_waitcnt lgkmcnt(2)
	v_cvt_pk_bf16_f32 v5, v6, v7
	s_waitcnt lgkmcnt(1)
	v_cvt_pk_bf16_f32 v6, v8, v9
	s_waitcnt lgkmcnt(0)
	v_cvt_pk_bf16_f32 v7, v10, v11
	global_store_dwordx4 v[12:13], v[4:7], off
	s_barrier

;   __device__ __forceinline__ u16* wt() const { return (u16*)(ws); }
;   if (ldb == 0) ldb = K;
;   float* lds = (float*)shm;
;   const int nTn = N >> 6;
;   const int tk = tile / nTn, tn = tile - tk * nTn;
;   const int k0 = tk * 64, n0 = tn * 64;
;   const int tid = opaque_tid(wv);
;   {
;     const int r = tid >> 4, c4 = (tid & 15) * 4;
; #pragma unroll
;     for (int i = 0; i < 2; ++i) {
;       float4 v = *(const float4*)(W + (long)(k0 + r + 32 * i) * N + n0 + c4);
;       float* d = lds + (r + 32 * i) * 65 + c4;
;       d[0] = v.x; d[1] = v.y; d[2] = v.z; d[3] = v.w;
;     }
;   }
;   __syncthreads();
;   {
;     const int n = tid >> 3, kq = (tid & 7) * 8;
;     float f[8];
; #pragma unroll
;     for (int j = 0; j < 8; ++j) f[j] = lds[(kq + j) * 65 + n];
;     if (gain) {
; #pragma unroll
;       for (int j = 0; j < 8; ++j) f[j] *= gain[k0 + kq + j];
;     }
;     u32x4 o = {pack2(f[0], f[1]), pack2(f[2], f[3]), pack2(f[4], f[5]), pack2(f[6], f[7])};
;     *(u32x4*)(Bt + (long)(n0 + n) * ldb + k0 + kq) = o;
;   }
;   __syncthreads();
; }
; __device__ __forceinline__ void convert_weights(const Params& p, int l, char* shm, int wv) {
;   u16* wb = p.wt() + (long)(l & 1) * WT_SET;
;   for (int g = opaque_bid(); g < 3648; g += gridDim.x) {
;     if (g < 1088) convert_tile(p.w_in + (long)l * 1024 * 4352, wb + O_IN, 1024, 4352, g, shm, p.mix_g + l * DM, wv);
.LBB0_24:
	s_andn2_b64 vcc, exec, s[16:17]
	s_cbranch_vccnz .LBB0_3
	s_mul_hi_i32 s14, s36, 0x78787879
	s_lshr_b32 s16, s14, 31
	s_ashr_i32 s14, s14, 5
	s_add_i32 s14, s14, s16
	s_mul_i32 s17, s14, 0xffffef00
	s_add_i32 s17, s21, s17
	s_add_i32 s36, s17, 0x29000
	s_ashr_i32 s37, s36, 31
	s_lshl_b32 s16, s14, 6
	v_mbcnt_lo_u32_b32 v2, -1, 0
	v_mbcnt_hi_u32_b32 v2, -1, v2
	s_lshl_b64 s[36:37], s[36:37], 2
	v_add_u32_e32 v12, s84, v2
	s_add_u32 s36, s44, s36
	v_lshlrev_b32_e32 v2, 4, v12
	v_ashrrev_i32_e32 v14, 4, v12
	s_addc_u32 s37, s45, s37
	v_and_b32_e32 v2, 0xf0, v2
	v_add_u32_e32 v10, s16, v14
	v_lshl_add_u64 v[8:9], s[36:37], 0, v[2:3]
	v_mad_i64_i32 v[4:5], s[36:37], v10, s35, v[8:9]
	global_load_dwordx4 v[4:7], v[4:5], off nt
	v_add_u32_e32 v10, 32, v10
	v_mad_i64_i32 v[8:9], s[36:37], v10, s35, v[8:9]
	global_load_dwordx4 v[8:11], v[8:9], off nt
	v_ashrrev_i32_e32 v13, 3, v12
	v_lshlrev_b32_e32 v12, 3, v12
	v_and_b32_e32 v12, 56, v12
	v_mad_u64_u32 v[14:15], s[36:37], v14, s26, v[2:3]
	v_mul_u32_u24_e32 v2, 0x104, v12
	v_lshl_add_u32 v2, v13, 2, v2
	v_add_u32_e32 v15, 0x2080, v14
	v_add_u32_e32 v16, 0x2088, v14
	v_add_u32_e32 v17, 0x400, v2
	s_andn2_b64 vcc, exec, s[12:13]
	s_waitcnt vmcnt(1)
	ds_write2_b32 v14, v4, v5 offset1:1
	ds_write2_b32 v14, v6, v7 offset0:2 offset1:3
	s_waitcnt vmcnt(0)
	ds_write2_b32 v15, v8, v9 offset1:1
	ds_write2_b32 v16, v10, v11 offset1:1
	s_waitcnt lgkmcnt(0)
	s_barrier
	ds_read2_b32 v[4:5], v2 offset1:65
	ds_read2_b32 v[6:7], v2 offset0:130 offset1:195
	ds_read2_b32 v[8:9], v17 offset0:4 offset1:69
	ds_read2_b32 v[10:11], v17 offset0:134 offset1:199
	s_cbranch_vccnz .LBB0_2
	v_or_b32_e32 v14, s16, v12
	v_ashrrev_i32_e32 v15, 31, v14
	v_lshl_add_u64 v[18:19], v[14:15], 2, s[42:43]
	global_load_dwordx4 v[14:17], v[18:19], off nt
	s_nop 0
	global_load_dwordx4 v[18:21], v[18:19], off offset:16
	s_waitcnt vmcnt(1) lgkmcnt(3)
	v_pk_mul_f32 v[4:5], v[4:5], v[14:15]
	s_waitcnt lgkmcnt(2)
	v_pk_mul_f32 v[6:7], v[6:7], v[16:17]
	s_waitcnt vmcnt(0) lgkmcnt(1)
	v_pk_mul_f32 v[8:9], v[8:9], v[18:19]
	s_waitcnt lgkmcnt(0)
	v_pk_mul_f32 v[10:11], v[10:11], v[20:21]
	s_branch .LBB0_2

;   __device__ __forceinline__ unsigned long long* ssq() const { return (unsigned long long*)(ws + 499 * MB); }
; __device__ __forceinline__ void init_rows(const float* __restrict__ x, u16* __restrict__ xb,
;                                           unsigned long long* __restrict__ ssq, int wv) {
;     ...
;   for (int row = blockIdx.x * 8 + wvi; row < T_TOK; row += gridDim.x * 8) {
;     const float* xr = x + (long)row * DM;
;     float4 v[4];
;     float ss = 0.f;
; #pragma unroll
;     for (int i = 0; i < 4; ++i) {
;       v[i] = *(const float4*)(xr + i * 256 + lane * 4);
;       ss += v[i].x * v[i].x + v[i].y * v[i].y + v[i].z * v[i].z + v[i].w * v[i].w;
;     }
; #pragma unroll
;     for (int o = 32; o >= 1; o >>= 1) ss += __shfl_xor(ss, o);
;     if (lane == 0) ssq[row] = (unsigned long long)(ss * SSQ_FIX);
.LBB0_30:
	v_ashrrev_i32_e32 v19, 31, v18
	v_lshlrev_b64 v[2:3], 12, v[18:19]
	v_lshl_add_u64 v[32:33], v[20:21], 0, v[2:3]
	global_load_dwordx4 v[2:5], v[32:33], off nt
	global_load_dwordx4 v[6:9], v[32:33], off offset:1024 nt
	global_load_dwordx4 v[10:13], v[32:33], off offset:2048 nt
	global_load_dwordx4 v[14:17], v[32:33], off offset:3072 nt
	s_waitcnt vmcnt(3)
	v_pk_mul_f32 v[32:33], v[2:3], v[2:3]
	s_waitcnt vmcnt(2)
	v_pk_mul_f32 v[36:37], v[6:7], v[6:7]
	v_pk_mul_f32 v[34:35], v[4:5], v[4:5]
	v_pk_mul_f32 v[38:39], v[8:9], v[8:9]
	s_waitcnt vmcnt(1)
	v_pk_mul_f32 v[40:41], v[10:11], v[10:11]
	v_add_f32_e32 v36, v36, v37
	v_add_f32_e32 v32, v32, v33
	v_pk_mul_f32 v[42:43], v[12:13], v[12:13]
	s_waitcnt vmcnt(0)
	v_pk_mul_f32 v[44:45], v[14:15], v[14:15]
	v_add_f32_e32 v33, v40, v41
	v_add_f32_e32 v36, v36, v38
	v_add_f32_e32 v32, v32, v34
	v_pk_mul_f32 v[46:47], v[16:17], v[16:17]
	v_add_f32_e32 v37, v44, v45
	v_add_f32_e32 v33, v33, v42
	v_add_f32_e32 v36, v36, v39
	v_add_f32_e32 v32, v32, v35
	v_add_f32_e32 v34, v37, v46
	v_add_f32_e32 v33, v33, v43
	v_add_f32_e32 v32, v32, v36
	v_add_f32_e32 v32, v32, v33
	v_add_f32_e32 v33, v34, v47
	v_add_f32_e32 v32, v32, v33
	ds_bpermute_b32 v33, v25, v32
	s_waitcnt lgkmcnt(0)
	v_add_f32_e32 v32, v32, v33
	ds_bpermute_b32 v33, v27, v32
	s_waitcnt lgkmcnt(0)
	v_add_f32_e32 v32, v32, v33
	ds_bpermute_b32 v33, v28, v32
	s_waitcnt lgkmcnt(0)
	v_add_f32_e32 v32, v32, v33
	ds_bpermute_b32 v33, v29, v32
	s_waitcnt lgkmcnt(0)
	v_add_f32_e32 v32, v32, v33
	ds_bpermute_b32 v33, v30, v32
	s_waitcnt lgkmcnt(0)
	v_add_f32_e32 v32, v32, v33
	ds_bpermute_b32 v33, v31, v32
	s_and_saveexec_b64 s[0:1], vcc
	s_cbranch_execz .LBB0_29
	s_waitcnt lgkmcnt(0)
	v_add_f32_e32 v32, v32, v33
	v_mul_f32_e32 v32, 0x49800000, v32
	v_trunc_f32_e32 v32, v32
	v_mul_f32_e32 v33, 0x2f800000, v32
	v_floor_f32_e32 v33, v33
	v_fmac_f32_e32 v32, 0xcf800000, v33
	v_cvt_u32_f32_e32 v32, v32
	v_cvt_u32_f32_e32 v33, v33
	v_lshl_add_u64 v[34:35], v[18:19], 3, s[10:11]
	global_store_dwordx2 v[34:35], v[32:33], off
	s_branch .LBB0_29

;   if (ldb == 0) ldb = K;
;   float* lds = (float*)shm;
;   const int nTn = N >> 6;
;   const int tk = tile / nTn, tn = tile - tk * nTn;
;   const int k0 = tk * 64, n0 = tn * 64;
;   const int tid = opaque_tid(wv);
;   {
;     const int r = tid >> 4, c4 = (tid & 15) * 4;
; #pragma unroll
;     for (int i = 0; i < 2; ++i) {
;       float4 v = *(const float4*)(W + (long)(k0 + r + 32 * i) * N + n0 + c4);
;       float* d = lds + (r + 32 * i) * 65 + c4;
;       d[0] = v.x; d[1] = v.y; d[2] = v.z; d[3] = v.w;
;     }
;   }
;   __syncthreads();
;   {
;     const int n = tid >> 3, kq = (tid & 7) * 8;
;     float f[8];
; #pragma unroll
;     for (int j = 0; j < 8; ++j) f[j] = lds[(kq + j) * 65 + n];
;     if (gain) {
; #pragma unroll
;       for (int j = 0; j < 8; ++j) f[j] *= gain[k0 + kq + j];
;     }
;     u32x4 o = {pack2(f[0], f[1]), pack2(f[2], f[3]), pack2(f[4], f[5]), pack2(f[6], f[7])};
;     *(u32x4*)(Bt + (long)(n0 + n) * ldb + k0 + kq) = o;
;   }
;   __syncthreads();
; }
.LBB0_795:
	s_add_i32 s71, s57, 0xa40
	s_cmpk_gt_i32 s71, 0x43f
	s_mov_b64 s[16:17], -1
	s_cbranch_scc0 .LBB0_815
	s_cmpk_gt_u32 s71, 0x4bf
	s_cbranch_scc0 .LBB0_812
	s_cmpk_gt_u32 s71, 0x53f
	s_cbranch_scc0 .LBB0_809
	s_cmpk_gt_u32 s71, 0x63f
	s_cbranch_scc0 .LBB0_806
	s_cmpk_gt_u32 s71, 0xa3f
	s_cbranch_scc0 .LBB0_801
	s_lshr_b32 s74, s57, 4
	s_lshl_b32 s16, s74, 10
	s_sub_i32 s16, s58, s16
	v_mbcnt_lo_u32_b32 v0, -1, 0
	v_mbcnt_hi_u32_b32 v0, -1, v0
	s_ashr_i32 s17, s16, 31
	v_add_u32_e32 v3, s84, v0
	s_lshl_b64 s[72:73], s[16:17], 2
	v_ashrrev_i32_e32 v7, 4, v3
	v_lshl_add_u32 v0, s74, 6, v7
	s_add_u32 s72, s20, s72
	v_lshlrev_b32_e32 v1, 4, v3
	s_addc_u32 s73, s21, s73
	v_and_b32_e32 v4, 0xf0, v1
	v_mov_b32_e32 v5, v2
	v_ashrrev_i32_e32 v1, 31, v0
	v_lshl_add_u64 v[8:9], s[72:73], 0, v[4:5]
	v_lshlrev_b64 v[0:1], 12, v[0:1]
	v_lshl_add_u64 v[0:1], v[8:9], 0, v[0:1]
	global_load_dwordx4 v[8:11], v[0:1], off nt
	s_movk_i32 s17, 0x104
	v_mad_u64_u32 v[4:5], s[72:73], v7, s17, v[4:5]
	v_add_co_u32_e32 v0, vcc, s87, v0
	v_ashrrev_i32_e32 v7, 3, v3
	s_nop 0
	v_addc_co_u32_e32 v1, vcc, 0, v1, vcc
	v_add_u32_e32 v5, 0x2080, v4
	s_mov_b32 s17, s52
	global_load_dwordx4 v[20:23], v[0:1], off nt
	s_waitcnt vmcnt(1)
	ds_write2_b32 v4, v8, v9 offset1:1
	ds_write2_b32 v4, v10, v11 offset0:2 offset1:3
	v_add_u32_e32 v0, 0x2088, v4
	s_waitcnt vmcnt(0)
	ds_write2_b32 v0, v22, v23 offset1:1
	v_lshlrev_b32_e32 v0, 3, v3
	v_and_b32_e32 v3, 56, v0
	v_mul_u32_u24_e32 v0, 0x104, v3
	ds_write2_b32 v5, v20, v21 offset1:1
	v_lshl_add_u32 v8, v7, 2, v0
	s_waitcnt lgkmcnt(0)
	s_barrier
	ds_read2_b32 v[0:1], v8 offset1:65
	ds_read2_b32 v[4:5], v8 offset0:130 offset1:195
	v_add_u32_e32 v8, 0x400, v8
	ds_read2_b32 v[10:11], v8 offset0:4 offset1:69
	ds_read2_b32 v[12:13], v8 offset0:134 offset1:199
	s_waitcnt lgkmcnt(3)
	v_cvt_pk_bf16_f32 v8, v0, v1
	v_add_u32_e32 v0, s16, v7
	v_ashrrev_i32_e32 v1, 31, v0
	v_lshlrev_b64 v[0:1], 13, v[0:1]
	v_lshl_add_u64 v[0:1], s[2:3], 0, v[0:1]
	s_lshl_b32 s16, s74, 7
	s_waitcnt lgkmcnt(2)
	v_cvt_pk_bf16_f32 v9, v4, v5
	v_lshl_add_u64 v[0:1], v[0:1], 0, s[16:17]
	v_lshlrev_b32_e32 v4, 1, v3
	v_mov_b32_e32 v5, v2
	s_waitcnt lgkmcnt(1)
	v_cvt_pk_bf16_f32 v10, v10, v11
	s_waitcnt lgkmcnt(0)
	v_cvt_pk_bf16_f32 v11, v12, v13
	v_lshl_add_u64 v[0:1], v[0:1], 0, v[4:5]
	global_store_dwordx4 v[0:1], v[8:11], off
	s_barrier
	s_mov_b64 s[16:17], 0
.LBB0_801:
	s_andn2_b64 vcc, exec, s[16:17]
	s_cbranch_vccnz .LBB0_805
	s_add_i32 s17, s58, 0x10000
	s_add_i32 s16, s57, 0x400
	s_and_b32 s17, s17, 0xfc0
	v_mbcnt_lo_u32_b32 v0, -1, 0
	v_mbcnt_hi_u32_b32 v0, -1, v0
	s_andn2_b32 s16, s16, 63
	v_add_u32_e32 v3, s84, v0
	s_lshl_b32 s72, s17, 2
	v_ashrrev_i32_e32 v7, 4, v3
	v_add_u32_e32 v0, s16, v7
	s_add_u32 s72, s22, s72
	v_lshlrev_b32_e32 v1, 4, v3
	s_addc_u32 s73, s23, 0
	v_and_b32_e32 v4, 0xf0, v1
	v_mov_b32_e32 v5, v2
	v_ashrrev_i32_e32 v1, 31, v0
	v_lshl_add_u64 v[8:9], s[72:73], 0, v[4:5]
	v_lshlrev_b64 v[0:1], 14, v[0:1]
	v_lshl_add_u64 v[0:1], v[8:9], 0, v[0:1]
	global_load_dwordx4 v[8:11], v[0:1], off nt
	s_movk_i32 s38, 0x104
	v_mad_u64_u32 v[4:5], s[72:73], v7, s38, v[4:5]
	s_mov_b32 s38, 0x80000
	v_add_co_u32_e32 v0, vcc, s38, v0
	v_ashrrev_i32_e32 v7, 3, v3
	s_nop 0
	v_addc_co_u32_e32 v1, vcc, 0, v1, vcc
	v_add_u32_e32 v5, 0x2080, v4
	v_readlane_b32 s38, v255, 16
	v_readlane_b32 s39, v255, 17
	s_andn2_b64 vcc, exec, s[38:39]
	global_load_dwordx4 v[20:23], v[0:1], off nt
	s_waitcnt vmcnt(1)
	ds_write2_b32 v4, v8, v9 offset1:1
	ds_write2_b32 v4, v10, v11 offset0:2 offset1:3
	v_add_u32_e32 v0, 0x2088, v4
	s_waitcnt vmcnt(0)
	ds_write2_b32 v0, v22, v23 offset1:1
	v_lshlrev_b32_e32 v0, 3, v3
	v_and_b32_e32 v3, 56, v0
	v_mul_u32_u24_e32 v0, 0x104, v3
	ds_write2_b32 v5, v20, v21 offset1:1
	v_lshl_add_u32 v8, v7, 2, v0
	v_add_u32_e32 v10, 0x400, v8
	s_waitcnt lgkmcnt(0)
	s_barrier
	ds_read2_b32 v[0:1], v8 offset1:65
	ds_read2_b32 v[4:5], v8 offset0:130 offset1:195
	ds_read2_b32 v[8:9], v10 offset0:4 offset1:69
	ds_read2_b32 v[10:11], v10 offset0:134 offset1:199
	s_cbranch_vccnz .LBB0_804
	v_or_b32_e32 v12, s16, v3
	v_mov_b32_e32 v13, v2
	v_lshl_add_u64 v[16:17], v[12:13], 2, s[12:13]
	global_load_dwordx4 v[12:15], v[16:17], off
	s_nop 0
	global_load_dwordx4 v[16:19], v[16:17], off offset:16
	s_waitcnt vmcnt(1) lgkmcnt(3)
	v_pk_mul_f32 v[0:1], v[0:1], v[12:13]
	s_waitcnt lgkmcnt(2)
	v_pk_mul_f32 v[4:5], v[4:5], v[14:15]
	s_waitcnt vmcnt(0) lgkmcnt(1)
	v_pk_mul_f32 v[8:9], v[8:9], v[16:17]
	s_waitcnt lgkmcnt(0)
	v_pk_mul_f32 v[10:11], v[10:11], v[18:19]

;   if (ldb == 0) ldb = K;
;   float* lds = (float*)shm;
;   const int nTn = N >> 6;
;   const int tk = tile / nTn, tn = tile - tk * nTn;
;   const int k0 = tk * 64, n0 = tn * 64;
;   const int tid = opaque_tid(wv);
;   {
;     const int r = tid >> 4, c4 = (tid & 15) * 4;
; #pragma unroll
;     for (int i = 0; i < 2; ++i) {
;       float4 v = *(const float4*)(W + (long)(k0 + r + 32 * i) * N + n0 + c4);
;       float* d = lds + (r + 32 * i) * 65 + c4;
;       d[0] = v.x; d[1] = v.y; d[2] = v.z; d[3] = v.w;
;     }
;   }
;   __syncthreads();
;   {
;     const int n = tid >> 3, kq = (tid & 7) * 8;
;     float f[8];
; #pragma unroll
;     for (int j = 0; j < 8; ++j) f[j] = lds[(kq + j) * 65 + n];
;     if (gain) {
; #pragma unroll
;       for (int j = 0; j < 8; ++j) f[j] *= gain[k0 + kq + j];
;     }
;     u32x4 o = {pack2(f[0], f[1]), pack2(f[2], f[3]), pack2(f[4], f[5]), pack2(f[6], f[7])};
;     *(u32x4*)(Bt + (long)(n0 + n) * ldb + k0 + kq) = o;
;   }
;   __syncthreads();
; }
.LBB0_806:
	s_andn2_b64 vcc, exec, s[16:17]
	s_cbranch_vccnz .LBB0_808
	s_lshl_b32 s16, s59, 6
	s_and_b32 s17, s16, 0xfffffc00
	s_sub_i32 s17, s58, s17
	s_lshl_b32 s16, s57, 2
	s_add_i32 s72, s17, 0x14000
	s_addk_i32 s16, 0x1400
	v_mbcnt_lo_u32_b32 v0, -1, 0
	v_mbcnt_hi_u32_b32 v0, -1, v0
	s_ashr_i32 s73, s72, 31
	v_add_u32_e32 v3, s84, v0
	s_andn2_b32 s16, s16, 63
	s_lshl_b64 s[74:75], s[72:73], 2
	v_ashrrev_i32_e32 v7, 4, v3
	v_add_u32_e32 v0, s16, v7
	s_add_u32 s74, s24, s74
	v_lshlrev_b32_e32 v1, 4, v3
	s_addc_u32 s75, s25, s75
	v_and_b32_e32 v4, 0xf0, v1
	v_mov_b32_e32 v5, v2
	v_ashrrev_i32_e32 v1, 31, v0
	v_lshl_add_u64 v[8:9], s[74:75], 0, v[4:5]
	v_lshlrev_b64 v[0:1], 12, v[0:1]
	v_lshl_add_u64 v[0:1], v[8:9], 0, v[0:1]
	global_load_dwordx4 v[8:11], v[0:1], off nt
	s_movk_i32 s17, 0x104
	v_mad_u64_u32 v[4:5], s[74:75], v7, s17, v[4:5]
	v_add_co_u32_e32 v0, vcc, s87, v0
	v_ashrrev_i32_e32 v7, 3, v3
	s_nop 0
	v_addc_co_u32_e32 v1, vcc, 0, v1, vcc
	v_add_u32_e32 v5, 0x2080, v4
	s_mov_b32 s17, s52
	global_load_dwordx4 v[20:23], v[0:1], off nt
	s_waitcnt vmcnt(1)
	ds_write2_b32 v4, v8, v9 offset1:1
	ds_write2_b32 v4, v10, v11 offset0:2 offset1:3
	v_add_u32_e32 v0, 0x2088, v4
	s_waitcnt vmcnt(0)
	ds_write2_b32 v0, v22, v23 offset1:1
	v_lshlrev_b32_e32 v0, 3, v3
	v_and_b32_e32 v3, 56, v0
	v_mul_u32_u24_e32 v0, 0x104, v3
	ds_write2_b32 v5, v20, v21 offset1:1
	v_lshl_add_u32 v8, v7, 2, v0
	s_waitcnt lgkmcnt(0)
	s_barrier
	ds_read2_b32 v[0:1], v8 offset1:65
	ds_read2_b32 v[4:5], v8 offset0:130 offset1:195
	v_add_u32_e32 v8, 0x400, v8
	ds_read2_b32 v[10:11], v8 offset0:4 offset1:69
	ds_read2_b32 v[12:13], v8 offset0:134 offset1:199
	s_waitcnt lgkmcnt(3)
	v_cvt_pk_bf16_f32 v8, v0, v1
	v_add_u32_e32 v0, s72, v7
	v_ashrrev_i32_e32 v1, 31, v0
	v_lshlrev_b64 v[0:1], 11, v[0:1]
	v_lshl_add_u64 v[0:1], s[6:7], 0, v[0:1]
	s_waitcnt lgkmcnt(2)
	v_cvt_pk_bf16_f32 v9, v4, v5
	v_lshl_add_u64 v[0:1], s[16:17], 1, v[0:1]
	v_lshlrev_b32_e32 v4, 1, v3
	v_mov_b32_e32 v5, v2
	s_waitcnt lgkmcnt(1)
	v_cvt_pk_bf16_f32 v10, v10, v11
	s_waitcnt lgkmcnt(0)
	v_cvt_pk_bf16_f32 v11, v12, v13
	v_lshl_add_u64 v[0:1], v[0:1], 0, v[4:5]
	global_store_dwordx4 v[0:1], v[8:11], off
	s_barrier

;   if (ldb == 0) ldb = K;
;   float* lds = (float*)shm;
;   const int nTn = N >> 6;
;   const int tk = tile / nTn, tn = tile - tk * nTn;
;   const int k0 = tk * 64, n0 = tn * 64;
;   const int tid = opaque_tid(wv);
;   {
;     const int r = tid >> 4, c4 = (tid & 15) * 4;
; #pragma unroll
;     for (int i = 0; i < 2; ++i) {
;       float4 v = *(const float4*)(W + (long)(k0 + r + 32 * i) * N + n0 + c4);
;       float* d = lds + (r + 32 * i) * 65 + c4;
;       d[0] = v.x; d[1] = v.y; d[2] = v.z; d[3] = v.w;
;     }
;   }
;   __syncthreads();
;   {
;     const int n = tid >> 3, kq = (tid & 7) * 8;
;     float f[8];
; #pragma unroll
;     for (int j = 0; j < 8; ++j) f[j] = lds[(kq + j) * 65 + n];
;     if (gain) {
; #pragma unroll
;       for (int j = 0; j < 8; ++j) f[j] *= gain[k0 + kq + j];
;     }
;     u32x4 o = {pack2(f[0], f[1]), pack2(f[2], f[3]), pack2(f[4], f[5]), pack2(f[6], f[7])};
;     *(u32x4*)(Bt + (long)(n0 + n) * ldb + k0 + kq) = o;
;   }
;   __syncthreads();
; }
.LBB0_809:
	s_andn2_b64 vcc, exec, s[16:17]
	s_cbranch_vccnz .LBB0_811
	s_lshl_b32 s17, s65, 6
	s_and_b32 s17, s17, 0xfffffc00
	s_sub_i32 s17, s58, s17
	s_lshl_b32 s16, s57, 2
	s_add_i32 s72, s17, 0x16000
	s_addk_i32 s16, 0x1600
	v_mbcnt_lo_u32_b32 v0, -1, 0
	v_mbcnt_hi_u32_b32 v0, -1, v0
	s_ashr_i32 s73, s72, 31
	v_add_u32_e32 v3, s84, v0
	s_andn2_b32 s16, s16, 63
	s_lshl_b64 s[74:75], s[72:73], 2
	v_ashrrev_i32_e32 v7, 4, v3
	v_add_u32_e32 v0, s16, v7
	s_add_u32 s74, s26, s74
	v_lshlrev_b32_e32 v1, 4, v3
	s_addc_u32 s75, s27, s75
	v_and_b32_e32 v4, 0xf0, v1
	v_mov_b32_e32 v5, v2
	v_ashrrev_i32_e32 v1, 31, v0
	v_lshl_add_u64 v[8:9], s[74:75], 0, v[4:5]
	v_lshlrev_b64 v[0:1], 12, v[0:1]
	v_lshl_add_u64 v[0:1], v[8:9], 0, v[0:1]
	global_load_dwordx4 v[8:11], v[0:1], off nt
	s_movk_i32 s17, 0x104
	v_mad_u64_u32 v[4:5], s[74:75], v7, s17, v[4:5]
	v_add_co_u32_e32 v0, vcc, s87, v0
	v_ashrrev_i32_e32 v7, 3, v3
	s_nop 0
	v_addc_co_u32_e32 v1, vcc, 0, v1, vcc
	v_add_u32_e32 v5, 0x2080, v4
	s_mov_b32 s17, s52
	global_load_dwordx4 v[20:23], v[0:1], off nt
	s_waitcnt vmcnt(1)
	ds_write2_b32 v4, v8, v9 offset1:1
	ds_write2_b32 v4, v10, v11 offset0:2 offset1:3
	v_add_u32_e32 v0, 0x2088, v4
	s_waitcnt vmcnt(0)
	ds_write2_b32 v0, v22, v23 offset1:1
	v_lshlrev_b32_e32 v0, 3, v3
	v_and_b32_e32 v3, 56, v0
	v_mul_u32_u24_e32 v0, 0x104, v3
	ds_write2_b32 v5, v20, v21 offset1:1
	v_lshl_add_u32 v8, v7, 2, v0
	s_waitcnt lgkmcnt(0)
	s_barrier
	ds_read2_b32 v[0:1], v8 offset1:65
	ds_read2_b32 v[4:5], v8 offset0:130 offset1:195
	v_add_u32_e32 v8, 0x400, v8
	ds_read2_b32 v[10:11], v8 offset0:4 offset1:69
	ds_read2_b32 v[12:13], v8 offset0:134 offset1:199
	s_waitcnt lgkmcnt(3)
	v_cvt_pk_bf16_f32 v8, v0, v1
	v_add_u32_e32 v0, s72, v7
	v_ashrrev_i32_e32 v1, 31, v0
	v_lshlrev_b64 v[0:1], 11, v[0:1]
	v_lshl_add_u64 v[0:1], s[8:9], 0, v[0:1]
	s_waitcnt lgkmcnt(2)
	v_cvt_pk_bf16_f32 v9, v4, v5
	v_lshl_add_u64 v[0:1], s[16:17], 1, v[0:1]
	v_lshlrev_b32_e32 v4, 1, v3
	v_mov_b32_e32 v5, v2
	s_waitcnt lgkmcnt(1)
	v_cvt_pk_bf16_f32 v10, v10, v11
	s_waitcnt lgkmcnt(0)
	v_cvt_pk_bf16_f32 v11, v12, v13
	v_lshl_add_u64 v[0:1], v[0:1], 0, v[4:5]
	global_store_dwordx4 v[0:1], v[8:11], off
	s_barrier

;   if (ldb == 0) ldb = K;
;   float* lds = (float*)shm;
;   const int nTn = N >> 6;
;   const int tk = tile / nTn, tn = tile - tk * nTn;
;   const int k0 = tk * 64, n0 = tn * 64;
;   const int tid = opaque_tid(wv);
;   {
;     const int r = tid >> 4, c4 = (tid & 15) * 4;
; #pragma unroll
;     for (int i = 0; i < 2; ++i) {
;       float4 v = *(const float4*)(W + (long)(k0 + r + 32 * i) * N + n0 + c4);
;       float* d = lds + (r + 32 * i) * 65 + c4;
;       d[0] = v.x; d[1] = v.y; d[2] = v.z; d[3] = v.w;
;     }
;   }
;   __syncthreads();
;   {
;     const int n = tid >> 3, kq = (tid & 7) * 8;
;     float f[8];
; #pragma unroll
;     for (int j = 0; j < 8; ++j) f[j] = lds[(kq + j) * 65 + n];
;     if (gain) {
; #pragma unroll
;       for (int j = 0; j < 8; ++j) f[j] *= gain[k0 + kq + j];
;     }
;     u32x4 o = {pack2(f[0], f[1]), pack2(f[2], f[3]), pack2(f[4], f[5]), pack2(f[6], f[7])};
;     *(u32x4*)(Bt + (long)(n0 + n) * ldb + k0 + kq) = o;
;   }
;   __syncthreads();
; }
.LBB0_812:
	s_andn2_b64 vcc, exec, s[16:17]
	s_cbranch_vccnz .LBB0_814
	s_lshl_b32 s16, s70, 6
	s_and_b32 s17, s16, 0xfffffc00
	s_sub_i32 s17, s58, s17
	s_lshl_b32 s16, s57, 2
	s_add_i32 s72, s17, 0x18000
	s_addk_i32 s16, 0x1800
	v_mbcnt_lo_u32_b32 v0, -1, 0
	v_mbcnt_hi_u32_b32 v0, -1, v0
	s_ashr_i32 s73, s72, 31
	v_add_u32_e32 v3, s84, v0
	s_andn2_b32 s16, s16, 63
	s_lshl_b64 s[74:75], s[72:73], 2
	v_ashrrev_i32_e32 v7, 4, v3
	v_add_u32_e32 v0, s16, v7
	s_add_u32 s74, s36, s74
	v_lshlrev_b32_e32 v1, 4, v3
	s_addc_u32 s75, s53, s75
	v_and_b32_e32 v4, 0xf0, v1
	v_mov_b32_e32 v5, v2
	v_ashrrev_i32_e32 v1, 31, v0
	v_lshl_add_u64 v[8:9], s[74:75], 0, v[4:5]
	v_lshlrev_b64 v[0:1], 12, v[0:1]
	v_lshl_add_u64 v[0:1], v[8:9], 0, v[0:1]
	global_load_dwordx4 v[8:11], v[0:1], off nt
	s_movk_i32 s17, 0x104
	v_mad_u64_u32 v[4:5], s[74:75], v7, s17, v[4:5]
	v_add_co_u32_e32 v0, vcc, s87, v0
	v_ashrrev_i32_e32 v7, 3, v3
	s_nop 0
	v_addc_co_u32_e32 v1, vcc, 0, v1, vcc
	v_add_u32_e32 v5, 0x2080, v4
	s_mov_b32 s17, s52
	global_load_dwordx4 v[20:23], v[0:1], off nt
	s_waitcnt vmcnt(1)
	ds_write2_b32 v4, v8, v9 offset1:1
	ds_write2_b32 v4, v10, v11 offset0:2 offset1:3
	v_add_u32_e32 v0, 0x2088, v4
	s_waitcnt vmcnt(0)
	ds_write2_b32 v0, v22, v23 offset1:1
	v_lshlrev_b32_e32 v0, 3, v3
	v_and_b32_e32 v3, 56, v0
	v_mul_u32_u24_e32 v0, 0x104, v3
	ds_write2_b32 v5, v20, v21 offset1:1
	v_lshl_add_u32 v8, v7, 2, v0
	s_waitcnt lgkmcnt(0)
	s_barrier
	ds_read2_b32 v[0:1], v8 offset1:65
	ds_read2_b32 v[4:5], v8 offset0:130 offset1:195
	v_add_u32_e32 v8, 0x400, v8
	ds_read2_b32 v[10:11], v8 offset0:4 offset1:69
	ds_read2_b32 v[12:13], v8 offset0:134 offset1:199
	s_waitcnt lgkmcnt(3)
	v_cvt_pk_bf16_f32 v8, v0, v1
	v_add_u32_e32 v0, s72, v7
	v_ashrrev_i32_e32 v1, 31, v0
	v_lshlrev_b64 v[0:1], 11, v[0:1]
	v_lshl_add_u64 v[0:1], s[10:11], 0, v[0:1]
	s_waitcnt lgkmcnt(2)
	v_cvt_pk_bf16_f32 v9, v4, v5
	v_lshl_add_u64 v[0:1], s[16:17], 1, v[0:1]
	v_lshlrev_b32_e32 v4, 1, v3
	v_mov_b32_e32 v5, v2
	s_waitcnt lgkmcnt(1)
	v_cvt_pk_bf16_f32 v10, v10, v11
	s_waitcnt lgkmcnt(0)
	v_cvt_pk_bf16_f32 v11, v12, v13
	v_lshl_add_u64 v[0:1], v[0:1], 0, v[4:5]
	global_store_dwordx4 v[0:1], v[8:11], off
	s_barrier

;   __device__ __forceinline__ u16* wt() const { return (u16*)(ws); }
;   if (ldb == 0) ldb = K;
;   float* lds = (float*)shm;
;   const int nTn = N >> 6;
;   const int tk = tile / nTn, tn = tile - tk * nTn;
;   const int k0 = tk * 64, n0 = tn * 64;
;   const int tid = opaque_tid(wv);
;   {
;     const int r = tid >> 4, c4 = (tid & 15) * 4;
; #pragma unroll
;     for (int i = 0; i < 2; ++i) {
;       float4 v = *(const float4*)(W + (long)(k0 + r + 32 * i) * N + n0 + c4);
;       float* d = lds + (r + 32 * i) * 65 + c4;
;       d[0] = v.x; d[1] = v.y; d[2] = v.z; d[3] = v.w;
;     }
;   }
;   __syncthreads();
;   {
;     const int n = tid >> 3, kq = (tid & 7) * 8;
;     float f[8];
; #pragma unroll
;     for (int j = 0; j < 8; ++j) f[j] = lds[(kq + j) * 65 + n];
;     if (gain) {
; #pragma unroll
;       for (int j = 0; j < 8; ++j) f[j] *= gain[k0 + kq + j];
;     }
;     u32x4 o = {pack2(f[0], f[1]), pack2(f[2], f[3]), pack2(f[4], f[5]), pack2(f[6], f[7])};
;     *(u32x4*)(Bt + (long)(n0 + n) * ldb + k0 + kq) = o;
;   }
;   __syncthreads();
; }
; __device__ __forceinline__ void convert_weights(const Params& p, int l, char* shm, int wv) {
;   u16* wb = p.wt() + (long)(l & 1) * WT_SET;
;   for (int g = opaque_bid(); g < 3648; g += gridDim.x) {
;     if (g < 1088) convert_tile(p.w_in + (long)l * 1024 * 4352, wb + O_IN, 1024, 4352, g, shm, p.mix_g + l * DM, wv);
.LBB0_815:
	s_andn2_b64 vcc, exec, s[16:17]
	s_cbranch_vccnz .LBB0_794
	s_mul_hi_i32 s16, s71, 0x78787879
	s_lshr_b32 s17, s16, 31
	s_ashr_i32 s16, s16, 5
	s_add_i32 s17, s16, s17
	s_mul_i32 s71, s17, 0xffffef00
	s_add_i32 s71, s58, s71
	s_add_i32 s72, s71, 0x29000
	s_ashr_i32 s73, s72, 31
	s_lshl_b32 s16, s17, 6
	v_mbcnt_lo_u32_b32 v0, -1, 0
	v_mbcnt_hi_u32_b32 v0, -1, v0
	s_lshl_b64 s[72:73], s[72:73], 2
	v_add_u32_e32 v3, s84, v0
	s_add_u32 s72, s54, s72
	v_lshlrev_b32_e32 v0, 4, v3
	v_ashrrev_i32_e32 v7, 4, v3
	s_addc_u32 s73, s55, s73
	v_and_b32_e32 v0, 0xf0, v0
	v_mov_b32_e32 v1, v2
	v_add_u32_e32 v12, s16, v7
	v_lshl_add_u64 v[4:5], s[72:73], 0, v[0:1]
	s_movk_i32 s42, 0x4400
	v_mad_i64_i32 v[8:9], s[72:73], v12, s42, v[4:5]
	global_load_dwordx4 v[8:11], v[8:9], off nt
	s_movk_i32 s39, 0x104
	v_mad_u64_u32 v[0:1], s[72:73], v7, s39, v[0:1]
	v_add_u32_e32 v1, 32, v12
	v_mad_i64_i32 v[4:5], s[72:73], v1, s42, v[4:5]
	v_add_u32_e32 v1, 0x2080, v0
	v_ashrrev_i32_e32 v7, 3, v3
	s_andn2_b64 vcc, exec, s[40:41]
	global_load_dwordx4 v[20:23], v[4:5], off nt
	s_waitcnt vmcnt(1)
	ds_write2_b32 v0, v8, v9 offset1:1
	ds_write2_b32 v0, v10, v11 offset0:2 offset1:3
	v_add_u32_e32 v0, 0x2088, v0
	s_waitcnt vmcnt(0)
	ds_write2_b32 v0, v22, v23 offset1:1
	v_lshlrev_b32_e32 v0, 3, v3
	v_and_b32_e32 v3, 56, v0
	v_mul_u32_u24_e32 v0, 0x104, v3
	ds_write2_b32 v1, v20, v21 offset1:1
	v_lshl_add_u32 v8, v7, 2, v0
	v_add_u32_e32 v10, 0x400, v8
	s_waitcnt lgkmcnt(0)
	s_barrier
	ds_read2_b32 v[0:1], v8 offset1:65
	ds_read2_b32 v[4:5], v8 offset0:130 offset1:195
	ds_read2_b32 v[8:9], v10 offset0:4 offset1:69
	ds_read2_b32 v[10:11], v10 offset0:134 offset1:199
	s_cbranch_vccnz .LBB0_793
	v_or_b32_e32 v12, s16, v3
	v_ashrrev_i32_e32 v13, 31, v12
	v_lshl_add_u64 v[16:17], v[12:13], 2, s[14:15]
	global_load_dwordx4 v[12:15], v[16:17], off
	s_nop 0
	global_load_dwordx4 v[16:19], v[16:17], off offset:16
	s_waitcnt vmcnt(1) lgkmcnt(3)
	v_pk_mul_f32 v[0:1], v[0:1], v[12:13]
	s_waitcnt lgkmcnt(2)
	v_pk_mul_f32 v[4:5], v[4:5], v[14:15]
	s_waitcnt vmcnt(0) lgkmcnt(1)
	v_pk_mul_f32 v[8:9], v[8:9], v[16:17]
	s_waitcnt lgkmcnt(0)
	v_pk_mul_f32 v[10:11], v[10:11], v[18:19]
	s_branch .LBB0_793
